# Q-load deserialize + two rows in flight in P1, P7, P11 streaming loops
# speedup vs baseline: 1.0080x; 1.0007x over previous
; __device__ __forceinline__ unsigned cvtpk(float lo, float hi) { unsigned r; asm volatile("v_cvt_pk_bf16_f32 %0, %1, %2" : "=v"(r) : "v"(lo), "v"(hi)); return r; }
; __device__ __forceinline__ void modnorm_phase(const Ctx& X, const float* src_p, const float* src_s, const float* g, const float* mod, int sh_off, int sc_off, bf16_t* H) {
;     ...
;         for (int r = 0; r < 16; ++r) {
;             const float* xr = src + (size_t)(t0 + r) * DM + X.lane * 4;
;             f32x4 v[4]; float ss = 0.f;
; #pragma unroll
;             for (int j = 0; j < 4; ++j) { v[j] = *(const f32x4*)(xr + 256 * j); ss += (v[j].x * v[j].x + v[j].y * v[j].y) + (v[j].z * v[j].z + v[j].w * v[j].w); }
;             const float rstd = rsqrtf(wave_sum(ss) * (1.f / DM) + EPS);
;             bf16_t* orow = H + (size_t)(t0 + r) * DM + X.lane * 4;
; #pragma unroll
;             for (int j = 0; j < 4; ++j) { const f32x4 o = v[j] * rstd * gs[j] + sh[j]; u32x2 w; w.x = cvtpk(o.x, o.y); w.y = cvtpk(o.z, o.w); *(u32x2*)(orow + 256 * j) = w; }
.LBB0_605:
	s_add_i32 s6, s3, s11
	s_ashr_i32 s7, s6, 31
	s_lshl_b64 s[12:13], s[6:7], 12
	v_lshl_add_u64 v[60:61], v[18:19], 0, s[12:13]
	global_load_dwordx4 v[44:47], v[60:61], off
	global_load_dwordx4 v[48:51], v[60:61], off offset:1024
	global_load_dwordx4 v[52:55], v[60:61], off offset:3072
	global_load_dwordx4 v[56:59], v[60:61], off offset:2048
	v_mov_b32_e32 v75, 0
	v_mov_b32_e32 v78, 0
	s_add_i32 s0, s6, 1
	s_lshl_b64 s[6:7], s[6:7], 11
	s_ashr_i32 s1, s0, 31
	v_lshl_add_u64 v[62:63], v[20:21], 0, s[6:7]
	s_lshl_b64 s[6:7], s[0:1], 12
	v_lshl_add_u64 v[60:61], v[18:19], 0, s[6:7]
	s_lshl_b64 s[0:1], s[0:1], 11
	global_load_dwordx4 v[84:87], v[60:61], off
	global_load_dwordx4 v[88:91], v[60:61], off offset:1024
	global_load_dwordx4 v[92:95], v[60:61], off offset:2048
	global_load_dwordx4 v[96:99], v[60:61], off offset:3072
	s_add_i32 s11, s11, 2
	s_cmp_eq_u32 s11, 16
	s_waitcnt vmcnt(7)
	v_pk_mul_f32 v[64:65], v[46:47], v[46:47]
	v_pk_mul_f32 v[66:67], v[44:45], v[44:45]
	s_waitcnt vmcnt(6)
	v_pk_mul_f32 v[68:69], v[50:51], v[50:51]
	v_pk_mul_f32 v[70:71], v[48:49], v[48:49]
	v_pk_mov_b32 v[76:77], v[66:67], v[64:65] op_sel:[1,0]
	v_mov_b32_e32 v67, v65
	v_pk_mov_b32 v[64:65], v[70:71], v[68:69] op_sel:[1,0]
	v_mov_b32_e32 v71, v69
	s_waitcnt vmcnt(4)
	v_mul_f32_e32 v72, v57, v57
	v_mul_f32_e32 v74, v59, v59
	v_pk_add_f32 v[66:67], v[76:77], v[66:67]
	v_pk_add_f32 v[64:65], v[64:65], v[70:71]
	v_mul_f32_e32 v79, v52, v52
	v_mul_f32_e32 v80, v53, v53
	v_mul_f32_e32 v81, v54, v54
	v_mul_f32_e32 v82, v55, v55
	v_pk_fma_f32 v[68:69], v[56:57], v[56:57], v[72:73] op_sel_hi:[1,1,0]
	v_pk_fma_f32 v[72:73], v[58:59], v[58:59], v[74:75] op_sel_hi:[1,1,0]
	v_pk_add_f32 v[66:67], v[66:67], v[66:67] op_sel:[0,1] op_sel_hi:[1,0]
	v_pk_add_f32 v[64:65], v[64:65], v[64:65] op_sel:[0,1] op_sel_hi:[1,0]
	v_mov_b32_e32 v69, v81
	v_mov_b32_e32 v73, v82
	v_mov_b32_e32 v67, v79
	v_mov_b32_e32 v65, v80
	v_pk_add_f32 v[68:69], v[68:69], v[72:73]
	v_pk_add_f32 v[64:65], v[66:67], v[64:65]
	v_mov_b32_e32 v73, 0
	v_pk_add_f32 v[64:65], v[64:65], v[68:69]
	v_mov_b32_e32 v76, 0
	v_add_f32_e32 v64, v64, v65
	s_nop 1
	v_add_f32_dpp v64, v64, v64 quad_perm:[1,0,3,2] row_mask:0xf bank_mask:0xf bound_ctrl:1
	s_nop 1
	v_add_f32_dpp v64, v64, v64 quad_perm:[2,3,0,1] row_mask:0xf bank_mask:0xf bound_ctrl:1
	s_nop 1
	v_add_f32_dpp v64, v64, v64 row_half_mirror row_mask:0xf bank_mask:0xf bound_ctrl:1
	s_nop 1
	v_add_f32_dpp v64, v64, v64 row_mirror row_mask:0xf bank_mask:0xf bound_ctrl:1
	s_nop 1
	v_mov_b32_dpp v75, v64 row_bcast:15 row_mask:0xa bank_mask:0xf
	v_add_f32_e32 v64, v64, v75
	s_nop 1
	v_mov_b32_dpp v78, v64 row_bcast:31 row_mask:0xc bank_mask:0xf
	v_add_f32_e32 v64, v64, v78
	s_nop 0
	v_readlane_b32 s6, v64, 63
	s_nop 1
	v_fma_f32 v64, s6, v43, v42
	v_mul_f32_e32 v65, 0x4b800000, v64
	v_cmp_gt_f32_e32 vcc, s9, v64
	s_nop 1
	v_cndmask_b32_e32 v64, v64, v65, vcc
	v_rsq_f32_e32 v64, v64
	s_nop 0
	v_mul_f32_e32 v65, 0x45800000, v64
	v_cndmask_b32_e32 v64, v64, v65, vcc
	v_pk_mul_f32 v[44:45], v[44:45], v[64:65] op_sel_hi:[1,0]
	v_pk_mul_f32 v[46:47], v[46:47], v[64:65] op_sel_hi:[1,0]
	v_pk_fma_f32 v[44:45], v[24:25], v[44:45], v[0:1]
	v_pk_mul_f32 v[48:49], v[48:49], v[64:65] op_sel_hi:[1,0]
	v_pk_mul_f32 v[50:51], v[50:51], v[64:65] op_sel_hi:[1,0]
	v_pk_fma_f32 v[46:47], v[22:23], v[46:47], v[2:3]
	v_cvt_pk_bf16_f32 v44, v44, v45
	v_pk_mul_f32 v[56:57], v[56:57], v[64:65] op_sel_hi:[1,0]
	v_cvt_pk_bf16_f32 v45, v46, v47
	v_pk_mul_f32 v[58:59], v[58:59], v[64:65] op_sel_hi:[1,0]
	v_pk_fma_f32 v[50:51], v[26:27], v[50:51], v[6:7]
	v_pk_fma_f32 v[48:49], v[28:29], v[48:49], v[4:5]
	global_store_dwordx2 v[62:63], v[44:45], off
	v_cvt_pk_bf16_f32 v44, v48, v49
	v_cvt_pk_bf16_f32 v45, v50, v51
	v_pk_mul_f32 v[52:53], v[52:53], v[64:65] op_sel_hi:[1,0]
	v_pk_mul_f32 v[54:55], v[54:55], v[64:65] op_sel_hi:[1,0]
	v_pk_fma_f32 v[58:59], v[30:31], v[58:59], v[10:11]
	v_pk_fma_f32 v[56:57], v[32:33], v[56:57], v[8:9]
	global_store_dwordx2 v[62:63], v[44:45], off offset:512
	v_cvt_pk_bf16_f32 v44, v56, v57
	v_cvt_pk_bf16_f32 v45, v58, v59
	v_pk_fma_f32 v[54:55], v[34:35], v[54:55], v[14:15]
	v_pk_fma_f32 v[52:53], v[36:37], v[52:53], v[12:13]
	global_store_dwordx2 v[62:63], v[44:45], off offset:1024
	v_cvt_pk_bf16_f32 v44, v52, v53
	v_cvt_pk_bf16_f32 v45, v54, v55
	global_store_dwordx2 v[62:63], v[44:45], off offset:1536
	v_lshl_add_u64 v[60:61], v[20:21], 0, s[0:1]
	s_waitcnt vmcnt(7)
; __device__ __forceinline__ unsigned cvtpk(float lo, float hi) { unsigned r; asm volatile("v_cvt_pk_bf16_f32 %0, %1, %2" : "=v"(r) : "v"(lo), "v"(hi)); return r; }
; __device__ __forceinline__ void modnorm_phase(const Ctx& X, const float* src_p, const float* src_s, const float* g, const float* mod, int sh_off, int sc_off, bf16_t* H) {
;     ...
;         for (int r = 0; r < 16; ++r) {
;             const float* xr = src + (size_t)(t0 + r) * DM + X.lane * 4;
;             f32x4 v[4]; float ss = 0.f;
; #pragma unroll
;             for (int j = 0; j < 4; ++j) { v[j] = *(const f32x4*)(xr + 256 * j); ss += (v[j].x * v[j].x + v[j].y * v[j].y) + (v[j].z * v[j].z + v[j].w * v[j].w); }
;             const float rstd = rsqrtf(wave_sum(ss) * (1.f / DM) + EPS);
;             bf16_t* orow = H + (size_t)(t0 + r) * DM + X.lane * 4;
; #pragma unroll
;             for (int j = 0; j < 4; ++j) { const f32x4 o = v[j] * rstd * gs[j] + sh[j]; u32x2 w; w.x = cvtpk(o.x, o.y); w.y = cvtpk(o.z, o.w); *(u32x2*)(orow + 256 * j) = w; }
	v_pk_mul_f32 v[62:63], v[86:87], v[86:87]
	v_pk_mul_f32 v[64:65], v[84:85], v[84:85]
	s_waitcnt vmcnt(6)
	v_pk_mul_f32 v[66:67], v[90:91], v[90:91]
	v_pk_mul_f32 v[68:69], v[88:89], v[88:89]
	v_pk_mov_b32 v[74:75], v[64:65], v[62:63] op_sel:[1,0]
	v_mov_b32_e32 v65, v63
	v_pk_mov_b32 v[62:63], v[68:69], v[66:67] op_sel:[1,0]
	v_mov_b32_e32 v69, v67
	s_waitcnt vmcnt(5)
	v_mul_f32_e32 v70, v93, v93
	v_mul_f32_e32 v72, v95, v95
	v_pk_add_f32 v[64:65], v[74:75], v[64:65]
	v_pk_add_f32 v[62:63], v[62:63], v[68:69]
	s_waitcnt vmcnt(4)
	v_mul_f32_e32 v77, v96, v96
	v_mul_f32_e32 v78, v97, v97
	v_mul_f32_e32 v79, v98, v98
	v_mul_f32_e32 v80, v99, v99
	v_pk_fma_f32 v[66:67], v[92:93], v[92:93], v[70:71] op_sel_hi:[1,1,0]
	v_pk_fma_f32 v[70:71], v[94:95], v[94:95], v[72:73] op_sel_hi:[1,1,0]
	v_pk_add_f32 v[64:65], v[64:65], v[64:65] op_sel:[0,1] op_sel_hi:[1,0]
	v_pk_add_f32 v[62:63], v[62:63], v[62:63] op_sel:[0,1] op_sel_hi:[1,0]
	v_mov_b32_e32 v67, v79
	v_mov_b32_e32 v71, v80
	v_mov_b32_e32 v65, v77
	v_mov_b32_e32 v63, v78
	v_pk_add_f32 v[66:67], v[66:67], v[70:71]
	v_pk_add_f32 v[62:63], v[64:65], v[62:63]
	s_nop 0
	v_pk_add_f32 v[62:63], v[62:63], v[66:67]
	s_nop 0
	v_add_f32_e32 v62, v62, v63
	s_nop 1
	v_add_f32_dpp v62, v62, v62 quad_perm:[1,0,3,2] row_mask:0xf bank_mask:0xf bound_ctrl:1
	s_nop 1
	v_add_f32_dpp v62, v62, v62 quad_perm:[2,3,0,1] row_mask:0xf bank_mask:0xf bound_ctrl:1
	s_nop 1
	v_add_f32_dpp v62, v62, v62 row_half_mirror row_mask:0xf bank_mask:0xf bound_ctrl:1
	s_nop 1
	v_add_f32_dpp v62, v62, v62 row_mirror row_mask:0xf bank_mask:0xf bound_ctrl:1
	s_nop 1
	v_mov_b32_dpp v73, v62 row_bcast:15 row_mask:0xa bank_mask:0xf
	v_add_f32_e32 v62, v62, v73
	s_nop 1
	v_mov_b32_dpp v76, v62 row_bcast:31 row_mask:0xc bank_mask:0xf
	v_add_f32_e32 v62, v62, v76
	s_nop 0
	v_readlane_b32 s0, v62, 63
	s_nop 1
	v_fma_f32 v62, s0, v43, v42
	v_mul_f32_e32 v63, 0x4b800000, v62
	v_cmp_gt_f32_e32 vcc, s9, v62
	s_nop 1
	v_cndmask_b32_e32 v62, v62, v63, vcc
	v_rsq_f32_e32 v62, v62
	s_nop 0
	v_mul_f32_e32 v63, 0x45800000, v62
	v_cndmask_b32_e32 v62, v62, v63, vcc
	v_pk_mul_f32 v[84:85], v[84:85], v[62:63] op_sel_hi:[1,0]
	v_pk_mul_f32 v[86:87], v[86:87], v[62:63] op_sel_hi:[1,0]
	v_pk_fma_f32 v[84:85], v[24:25], v[84:85], v[0:1]
	v_pk_mul_f32 v[88:89], v[88:89], v[62:63] op_sel_hi:[1,0]
	v_pk_mul_f32 v[90:91], v[90:91], v[62:63] op_sel_hi:[1,0]
	v_pk_fma_f32 v[86:87], v[22:23], v[86:87], v[2:3]
	v_cvt_pk_bf16_f32 v84, v84, v85
	v_pk_mul_f32 v[92:93], v[92:93], v[62:63] op_sel_hi:[1,0]
	v_cvt_pk_bf16_f32 v85, v86, v87
	v_pk_mul_f32 v[94:95], v[94:95], v[62:63] op_sel_hi:[1,0]
	v_pk_fma_f32 v[90:91], v[26:27], v[90:91], v[6:7]
	v_pk_fma_f32 v[88:89], v[28:29], v[88:89], v[4:5]
	global_store_dwordx2 v[60:61], v[84:85], off
	v_cvt_pk_bf16_f32 v84, v88, v89
	v_cvt_pk_bf16_f32 v85, v90, v91
	v_pk_mul_f32 v[96:97], v[96:97], v[62:63] op_sel_hi:[1,0]
	v_pk_mul_f32 v[98:99], v[98:99], v[62:63] op_sel_hi:[1,0]
	v_pk_fma_f32 v[94:95], v[30:31], v[94:95], v[10:11]
	v_pk_fma_f32 v[92:93], v[32:33], v[92:93], v[8:9]
	global_store_dwordx2 v[60:61], v[84:85], off offset:512
	v_cvt_pk_bf16_f32 v84, v92, v93
	v_cvt_pk_bf16_f32 v85, v94, v95
	v_pk_fma_f32 v[98:99], v[34:35], v[98:99], v[14:15]
	v_pk_fma_f32 v[96:97], v[36:37], v[96:97], v[12:13]
	global_store_dwordx2 v[60:61], v[84:85], off offset:1024
	v_cvt_pk_bf16_f32 v84, v96, v97
	v_cvt_pk_bf16_f32 v85, v98, v99
	global_store_dwordx2 v[60:61], v[84:85], off offset:1536
	s_cbranch_scc0 .LBB0_605
	s_add_i32 s10, s10, s87
	s_add_i32 s3, s3, s8
	s_cmpk_gt_i32 s10, 0x17ff
	s_cbranch_scc0 .LBB0_604

; __device__ __forceinline__ void final_norm_phase(const Ctx& X, float* out, const float* g) {
;     ...
;         for (int r = 0; r < 16; ++r) { float* xr = out + (size_t)(ch * 16 + r) * DM + X.lane * 4;
;             f32x4 v[4]; float ss = 0.f;
; #pragma unroll
;             for (int j = 0; j < 4; ++j) { v[j] = *(const f32x4*)(xr + 256 * j); ss += (v[j].x * v[j].x + v[j].y * v[j].y) + (v[j].z * v[j].z + v[j].w * v[j].w); }
;             const float rstd = rsqrtf(wave_sum(ss) * (1.f / DM) + EPS);
; #pragma unroll
;             for (int j = 0; j < 4; ++j) *(f32x4*)(xr + 256 * j) = v[j] * rstd * gv[j]; }
.LBB0_885:
	global_load_dwordx4 v[24:27], v[20:21], off offset:-2048
	global_load_dwordx4 v[28:31], v[20:21], off offset:-1024
	global_load_dwordx4 v[32:35], v[20:21], off offset:1024
	global_load_dwordx4 v[36:39], v[20:21], off
	v_mov_b32_e32 v53, 0
	v_mov_b32_e32 v56, 0
	s_add_i32 s8, s4, s1
	s_ashr_i32 s9, s8, 31
	s_lshl_b64 s[8:9], s[8:9], 12
	v_lshl_add_u64 v[40:41], v[16:17], 0, s[8:9]
	global_load_dwordx4 v[64:67], v[40:41], off
	global_load_dwordx4 v[68:71], v[40:41], off offset:1024
	global_load_dwordx4 v[72:75], v[40:41], off offset:2048
	global_load_dwordx4 v[76:79], v[40:41], off offset:3072
	s_add_i32 s1, s1, 2
	s_cmp_eq_u32 s1, 16
	s_waitcnt vmcnt(7)
	v_pk_mul_f32 v[42:43], v[26:27], v[26:27]
	v_pk_mul_f32 v[44:45], v[24:25], v[24:25]
	s_waitcnt vmcnt(6)
	v_pk_mul_f32 v[46:47], v[30:31], v[30:31]
	v_pk_mul_f32 v[48:49], v[28:29], v[28:29]
	v_pk_mov_b32 v[54:55], v[44:45], v[42:43] op_sel:[1,0]
	v_mov_b32_e32 v45, v43
	v_pk_mov_b32 v[42:43], v[48:49], v[46:47] op_sel:[1,0]
	v_mov_b32_e32 v49, v47
	s_waitcnt vmcnt(4)
	v_mul_f32_e32 v50, v37, v37
	v_mul_f32_e32 v52, v39, v39
	v_pk_add_f32 v[44:45], v[54:55], v[44:45]
	v_pk_add_f32 v[42:43], v[42:43], v[48:49]
	v_mul_f32_e32 v57, v32, v32
	v_mul_f32_e32 v58, v33, v33
	v_mul_f32_e32 v59, v34, v34
	v_mul_f32_e32 v60, v35, v35
	v_pk_fma_f32 v[46:47], v[36:37], v[36:37], v[50:51] op_sel_hi:[1,1,0]
	v_pk_fma_f32 v[50:51], v[38:39], v[38:39], v[52:53] op_sel_hi:[1,1,0]
	v_pk_add_f32 v[44:45], v[44:45], v[44:45] op_sel:[0,1] op_sel_hi:[1,0]
	v_pk_add_f32 v[42:43], v[42:43], v[42:43] op_sel:[0,1] op_sel_hi:[1,0]
	v_mov_b32_e32 v47, v59
	v_mov_b32_e32 v51, v60
	v_mov_b32_e32 v45, v57
	v_mov_b32_e32 v43, v58
	v_pk_add_f32 v[46:47], v[46:47], v[50:51]
	v_pk_add_f32 v[42:43], v[44:45], v[42:43]
	s_nop 0
	v_pk_add_f32 v[42:43], v[42:43], v[46:47]
	s_nop 0
	v_add_f32_e32 v42, v42, v43
	s_nop 1
	v_add_f32_dpp v42, v42, v42 quad_perm:[1,0,3,2] row_mask:0xf bank_mask:0xf bound_ctrl:1
	s_nop 1
	v_add_f32_dpp v42, v42, v42 quad_perm:[2,3,0,1] row_mask:0xf bank_mask:0xf bound_ctrl:1
	s_nop 1
	v_add_f32_dpp v42, v42, v42 row_half_mirror row_mask:0xf bank_mask:0xf bound_ctrl:1
	s_nop 1
	v_add_f32_dpp v42, v42, v42 row_mirror row_mask:0xf bank_mask:0xf bound_ctrl:1
	s_nop 1
	v_mov_b32_dpp v53, v42 row_bcast:15 row_mask:0xa bank_mask:0xf
	v_add_f32_e32 v42, v42, v53
	v_mov_b32_e32 v53, 0
	s_nop 0
	v_mov_b32_dpp v56, v42 row_bcast:31 row_mask:0xc bank_mask:0xf
	v_add_f32_e32 v42, v42, v56
	v_mov_b32_e32 v56, 0
	v_readlane_b32 s7, v42, 63
	s_nop 1
	v_fma_f32 v42, s7, v23, v22
	v_mul_f32_e32 v43, 0x4b800000, v42
	v_cmp_gt_f32_e32 vcc, s6, v42
	s_nop 1
	v_cndmask_b32_e32 v42, v42, v43, vcc
	v_rsq_f32_e32 v42, v42
	s_nop 0
	v_mul_f32_e32 v43, 0x45800000, v42
	v_cndmask_b32_e32 v42, v42, v43, vcc
	v_pk_mul_f32 v[24:25], v[24:25], v[42:43] op_sel_hi:[1,0]
	v_pk_mul_f32 v[26:27], v[26:27], v[42:43] op_sel_hi:[1,0]
	v_pk_mul_f32 v[28:29], v[28:29], v[42:43] op_sel_hi:[1,0]
	v_pk_mul_f32 v[30:31], v[30:31], v[42:43] op_sel_hi:[1,0]
	v_pk_mul_f32 v[36:37], v[36:37], v[42:43] op_sel_hi:[1,0]
	v_pk_mul_f32 v[38:39], v[38:39], v[42:43] op_sel_hi:[1,0]
	v_pk_mul_f32 v[44:45], v[32:33], v[42:43] op_sel_hi:[1,0]
	v_pk_mul_f32 v[42:43], v[34:35], v[42:43] op_sel_hi:[1,0]
	v_pk_mul_f32 v[26:27], v[2:3], v[26:27]
	v_pk_mul_f32 v[24:25], v[0:1], v[24:25]
	v_pk_mul_f32 v[30:31], v[6:7], v[30:31]
	v_pk_mul_f32 v[28:29], v[4:5], v[28:29]
	v_pk_mul_f32 v[34:35], v[10:11], v[38:39]
	v_pk_mul_f32 v[32:33], v[8:9], v[36:37]
	v_pk_mul_f32 v[38:39], v[14:15], v[42:43]
	v_pk_mul_f32 v[36:37], v[12:13], v[44:45]
	global_store_dwordx4 v[20:21], v[24:27], off offset:-2048
	global_store_dwordx4 v[20:21], v[28:31], off offset:-1024
	global_store_dwordx4 v[20:21], v[32:35], off
	global_store_dwordx4 v[20:21], v[36:39], off offset:1024
	v_lshl_add_u64 v[20:21], v[20:21], 0, s[2:3]
	s_waitcnt vmcnt(7)
	v_pk_mul_f32 v[42:43], v[66:67], v[66:67]
	v_pk_mul_f32 v[44:45], v[64:65], v[64:65]
	s_waitcnt vmcnt(6)
	v_pk_mul_f32 v[46:47], v[70:71], v[70:71]
	v_pk_mul_f32 v[48:49], v[68:69], v[68:69]
	v_pk_mov_b32 v[54:55], v[44:45], v[42:43] op_sel:[1,0]
	v_mov_b32_e32 v45, v43
	v_pk_mov_b32 v[42:43], v[48:49], v[46:47] op_sel:[1,0]
	v_mov_b32_e32 v49, v47
	s_waitcnt vmcnt(5)
	v_mul_f32_e32 v50, v73, v73
	v_mul_f32_e32 v52, v75, v75
	v_pk_add_f32 v[44:45], v[54:55], v[44:45]
	v_pk_add_f32 v[42:43], v[42:43], v[48:49]
	s_waitcnt vmcnt(4)
	v_mul_f32_e32 v57, v76, v76
	v_mul_f32_e32 v58, v77, v77
	v_mul_f32_e32 v59, v78, v78
	v_mul_f32_e32 v60, v79, v79
	v_pk_fma_f32 v[46:47], v[72:73], v[72:73], v[50:51] op_sel_hi:[1,1,0]
	v_pk_fma_f32 v[50:51], v[74:75], v[74:75], v[52:53] op_sel_hi:[1,1,0]
	v_pk_add_f32 v[44:45], v[44:45], v[44:45] op_sel:[0,1] op_sel_hi:[1,0]
	v_pk_add_f32 v[42:43], v[42:43], v[42:43] op_sel:[0,1] op_sel_hi:[1,0]
	v_mov_b32_e32 v47, v59
	v_mov_b32_e32 v51, v60
	v_mov_b32_e32 v45, v57
	v_mov_b32_e32 v43, v58
	v_pk_add_f32 v[46:47], v[46:47], v[50:51]
	v_pk_add_f32 v[42:43], v[44:45], v[42:43]
	s_nop 0
	v_pk_add_f32 v[42:43], v[42:43], v[46:47]
	s_nop 0
	v_add_f32_e32 v42, v42, v43
	s_nop 1
	v_add_f32_dpp v42, v42, v42 quad_perm:[1,0,3,2] row_mask:0xf bank_mask:0xf bound_ctrl:1
	s_nop 1
	v_add_f32_dpp v42, v42, v42 quad_perm:[2,3,0,1] row_mask:0xf bank_mask:0xf bound_ctrl:1
	s_nop 1
	v_add_f32_dpp v42, v42, v42 row_half_mirror row_mask:0xf bank_mask:0xf bound_ctrl:1
	s_nop 1
	v_add_f32_dpp v42, v42, v42 row_mirror row_mask:0xf bank_mask:0xf bound_ctrl:1
	s_nop 1
	v_mov_b32_dpp v53, v42 row_bcast:15 row_mask:0xa bank_mask:0xf
	v_add_f32_e32 v42, v42, v53
	s_nop 1
	v_mov_b32_dpp v56, v42 row_bcast:31 row_mask:0xc bank_mask:0xf
	v_add_f32_e32 v42, v42, v56
	s_nop 0
	v_readlane_b32 s7, v42, 63
	s_nop 1
	v_fma_f32 v42, s7, v23, v22
	v_mul_f32_e32 v43, 0x4b800000, v42
	v_cmp_gt_f32_e32 vcc, s6, v42
	s_nop 1
	v_cndmask_b32_e32 v42, v42, v43, vcc
	v_rsq_f32_e32 v42, v42
	s_nop 0
	v_mul_f32_e32 v43, 0x45800000, v42
	v_cndmask_b32_e32 v42, v42, v43, vcc
	v_pk_mul_f32 v[64:65], v[64:65], v[42:43] op_sel_hi:[1,0]
	v_pk_mul_f32 v[66:67], v[66:67], v[42:43] op_sel_hi:[1,0]
	v_pk_mul_f32 v[68:69], v[68:69], v[42:43] op_sel_hi:[1,0]
	v_pk_mul_f32 v[70:71], v[70:71], v[42:43] op_sel_hi:[1,0]
	v_pk_mul_f32 v[72:73], v[72:73], v[42:43] op_sel_hi:[1,0]
	v_pk_mul_f32 v[74:75], v[74:75], v[42:43] op_sel_hi:[1,0]
	v_pk_mul_f32 v[76:77], v[76:77], v[42:43] op_sel_hi:[1,0]
	v_pk_mul_f32 v[78:79], v[78:79], v[42:43] op_sel_hi:[1,0]
	v_pk_mul_f32 v[66:67], v[2:3], v[66:67]
	v_pk_mul_f32 v[64:65], v[0:1], v[64:65]
	v_pk_mul_f32 v[70:71], v[6:7], v[70:71]
	v_pk_mul_f32 v[68:69], v[4:5], v[68:69]
	v_pk_mul_f32 v[74:75], v[10:11], v[74:75]
	v_pk_mul_f32 v[72:73], v[8:9], v[72:73]
	v_pk_mul_f32 v[78:79], v[14:15], v[78:79]
	v_pk_mul_f32 v[76:77], v[12:13], v[76:77]
	global_store_dwordx4 v[40:41], v[64:67], off
	global_store_dwordx4 v[40:41], v[68:71], off offset:1024
	global_store_dwordx4 v[40:41], v[72:75], off offset:2048
	global_store_dwordx4 v[40:41], v[76:79], off offset:3072
	s_cbranch_scc0 .LBB0_885
; __device__ __forceinline__ void final_norm_phase(const Ctx& X, float* out, const float* g) {
;     ...
;     for (int ch = X.gw; ch < T_ALL / 16; ch += X.NGW) {
; #pragma unroll 2
;         for (int r = 0; r < 16; ++r) { float* xr = out + (size_t)(ch * 16 + r) * DM + X.lane * 4;
	s_add_i32 s86, s86, s87
	s_add_i32 s4, s4, s5
	s_add_i32 s0, s0, s5
	s_cmpk_gt_i32 s86, 0x17ff
	s_cbranch_scc0 .LBB0_884
